# phase0 silu loads de-serialised + lambda moved to idle block + GEMM2 epilogue residual loads prefetched 12 deep
# speedup vs baseline: 1.0043x; 1.0043x over previous
; #define LAS __attribute__((address_space(3)))
; __device__ __forceinline__ void phase0(const Args& A, LAS unsigned char* lds) {
;     ...
;         LAS float* sc = (LAS float*)lds;
;         for (int i = tid; i < 8192; i += 512) { const float v = A.c[i]; sc[i] = v * __builtin_amdgcn_rcpf(1.f + __expf(-v)); }
;         __syncthreads();
.LBB0_17:
	s_or_b64 exec, exec, s[4:5]
	s_load_dwordx16 s[52:67], s[0:1], 0x0
	s_add_u32 s86, s50, 0x1000
	s_addc_u32 s87, s51, 0
	v_mov_b32_e32 v44, v214
	s_cmpk_gt_i32 s2, 0xbf
	s_cbranch_scc1 .LBB0_25
	s_movk_i32 s4, 0x2000
	v_cmp_gt_i32_e32 vcc, s4, v44
	s_and_saveexec_b64 s[4:5], vcc
	s_cbranch_execz .LBB0_21
	s_waitcnt lgkmcnt(0)
	v_lshlrev_b32_e32 v0, 2, v44
	v_lshl_add_u32 v3, v44, 2, 0
	global_load_dword v4, v0, s[54:55]
	global_load_dword v5, v0, s[54:55] offset:2048
	v_add_u32_e32 v0, 0x1000, v0
	global_load_dword v6, v0, s[54:55]
	global_load_dword v7, v0, s[54:55] offset:2048
	v_add_u32_e32 v0, 0x1000, v0
	global_load_dword v8, v0, s[54:55]
	global_load_dword v9, v0, s[54:55] offset:2048
	v_add_u32_e32 v0, 0x1000, v0
	global_load_dword v10, v0, s[54:55]
	global_load_dword v11, v0, s[54:55] offset:2048
	v_add_u32_e32 v0, 0x1000, v0
	global_load_dword v12, v0, s[54:55]
	global_load_dword v13, v0, s[54:55] offset:2048
	v_add_u32_e32 v0, 0x1000, v0
	global_load_dword v14, v0, s[54:55]
	global_load_dword v15, v0, s[54:55] offset:2048
	v_add_u32_e32 v0, 0x1000, v0
	global_load_dword v16, v0, s[54:55]
	global_load_dword v17, v0, s[54:55] offset:2048
	v_add_u32_e32 v0, 0x1000, v0
	global_load_dword v18, v0, s[54:55]
	global_load_dword v19, v0, s[54:55] offset:2048
	s_waitcnt vmcnt(15)
	v_mul_f32_e32 v20, 0xbfb8aa3b, v4
	v_exp_f32_e32 v20, v20
	s_nop 0
	v_add_f32_e32 v20, 1.0, v20
	v_rcp_f32_e32 v20, v20
	s_nop 0
	v_mul_f32_e32 v4, v4, v20
	ds_write_b32 v3, v4 offset:0
	s_waitcnt vmcnt(14)
	v_mul_f32_e32 v20, 0xbfb8aa3b, v5
	v_exp_f32_e32 v20, v20
	s_nop 0
	v_add_f32_e32 v20, 1.0, v20
	v_rcp_f32_e32 v20, v20
	s_nop 0
	v_mul_f32_e32 v5, v5, v20
	ds_write_b32 v3, v5 offset:2048
	s_waitcnt vmcnt(13)
	v_mul_f32_e32 v20, 0xbfb8aa3b, v6
	v_exp_f32_e32 v20, v20
	s_nop 0
	v_add_f32_e32 v20, 1.0, v20
	v_rcp_f32_e32 v20, v20
	s_nop 0
	v_mul_f32_e32 v6, v6, v20
	ds_write_b32 v3, v6 offset:4096
	s_waitcnt vmcnt(12)
	v_mul_f32_e32 v20, 0xbfb8aa3b, v7
	v_exp_f32_e32 v20, v20
	s_nop 0
	v_add_f32_e32 v20, 1.0, v20
	v_rcp_f32_e32 v20, v20
	s_nop 0
	v_mul_f32_e32 v7, v7, v20
	ds_write_b32 v3, v7 offset:6144
	s_waitcnt vmcnt(11)
	v_mul_f32_e32 v20, 0xbfb8aa3b, v8
	v_exp_f32_e32 v20, v20
	s_nop 0
	v_add_f32_e32 v20, 1.0, v20
	v_rcp_f32_e32 v20, v20
	s_nop 0
	v_mul_f32_e32 v8, v8, v20
	ds_write_b32 v3, v8 offset:8192
	s_waitcnt vmcnt(10)
	v_mul_f32_e32 v20, 0xbfb8aa3b, v9
	v_exp_f32_e32 v20, v20
	s_nop 0
	v_add_f32_e32 v20, 1.0, v20
	v_rcp_f32_e32 v20, v20
	s_nop 0
	v_mul_f32_e32 v9, v9, v20
	ds_write_b32 v3, v9 offset:10240
	s_waitcnt vmcnt(9)
	v_mul_f32_e32 v20, 0xbfb8aa3b, v10
	v_exp_f32_e32 v20, v20
	s_nop 0
	v_add_f32_e32 v20, 1.0, v20
	v_rcp_f32_e32 v20, v20
	s_nop 0
	v_mul_f32_e32 v10, v10, v20
	ds_write_b32 v3, v10 offset:12288
	s_waitcnt vmcnt(8)
	v_mul_f32_e32 v20, 0xbfb8aa3b, v11
	v_exp_f32_e32 v20, v20
	s_nop 0
	v_add_f32_e32 v20, 1.0, v20
	v_rcp_f32_e32 v20, v20
	s_nop 0
	v_mul_f32_e32 v11, v11, v20
	ds_write_b32 v3, v11 offset:14336
	s_waitcnt vmcnt(7)
	v_mul_f32_e32 v20, 0xbfb8aa3b, v12
	v_exp_f32_e32 v20, v20
	s_nop 0
	v_add_f32_e32 v20, 1.0, v20
	v_rcp_f32_e32 v20, v20
	s_nop 0
	v_mul_f32_e32 v12, v12, v20
	ds_write_b32 v3, v12 offset:16384
	s_waitcnt vmcnt(6)
	v_mul_f32_e32 v20, 0xbfb8aa3b, v13
	v_exp_f32_e32 v20, v20
	s_nop 0
	v_add_f32_e32 v20, 1.0, v20
	v_rcp_f32_e32 v20, v20
	s_nop 0
	v_mul_f32_e32 v13, v13, v20
	ds_write_b32 v3, v13 offset:18432
	s_waitcnt vmcnt(5)
	v_mul_f32_e32 v20, 0xbfb8aa3b, v14
	v_exp_f32_e32 v20, v20
	s_nop 0
	v_add_f32_e32 v20, 1.0, v20
	v_rcp_f32_e32 v20, v20
	s_nop 0
	v_mul_f32_e32 v14, v14, v20
	ds_write_b32 v3, v14 offset:20480
	s_waitcnt vmcnt(4)
	v_mul_f32_e32 v20, 0xbfb8aa3b, v15
	v_exp_f32_e32 v20, v20
	s_nop 0
	v_add_f32_e32 v20, 1.0, v20
	v_rcp_f32_e32 v20, v20
	s_nop 0
	v_mul_f32_e32 v15, v15, v20
	ds_write_b32 v3, v15 offset:22528
	s_waitcnt vmcnt(3)
	v_mul_f32_e32 v20, 0xbfb8aa3b, v16
	v_exp_f32_e32 v20, v20
	s_nop 0
	v_add_f32_e32 v20, 1.0, v20
	v_rcp_f32_e32 v20, v20
	s_nop 0
	v_mul_f32_e32 v16, v16, v20
	ds_write_b32 v3, v16 offset:24576
	s_waitcnt vmcnt(2)
	v_mul_f32_e32 v20, 0xbfb8aa3b, v17
	v_exp_f32_e32 v20, v20
	s_nop 0
	v_add_f32_e32 v20, 1.0, v20
	v_rcp_f32_e32 v20, v20
	s_nop 0
	v_mul_f32_e32 v17, v17, v20
	ds_write_b32 v3, v17 offset:26624
	s_waitcnt vmcnt(1)
	v_mul_f32_e32 v20, 0xbfb8aa3b, v18
	v_exp_f32_e32 v20, v20
	s_nop 0
	v_add_f32_e32 v20, 1.0, v20
	v_rcp_f32_e32 v20, v20
	s_nop 0
	v_mul_f32_e32 v18, v18, v20
	ds_write_b32 v3, v18 offset:28672
	s_waitcnt vmcnt(0)
	v_mul_f32_e32 v20, 0xbfb8aa3b, v19
	v_exp_f32_e32 v20, v20
	s_nop 0
	v_add_f32_e32 v20, 1.0, v20
	v_rcp_f32_e32 v20, v20
	s_nop 0
	v_mul_f32_e32 v19, v19, v20
	ds_write_b32 v3, v19 offset:30720

; __device__ __forceinline__ void phase0(const Args& A, LAS unsigned char* lds) {
;     ...
;     if (blockIdx.x == 0 && tid == 0) {
;         float s1 = 0.f, s2 = 0.f;
;         for (int i = 0; i < 64; ++i) { s1 += A.lq1[i] * A.lk1[i]; s2 += A.lq2[i] * A.lk2[i]; }
;         ((float*)(A.ws + WS_CTL))[1] = expf(s1) - expf(s2) + 0.2f;
;         ((unsigned*)(A.ws + WS_CTL))[0] = 0u; ((unsigned*)(A.ws + WS_CTL))[2] = 0u;
;     }
.LBB0_28:
	s_or_b64 exec, exec, s[4:5]
	s_load_dwordx16 s[68:83], s[0:1], 0x40
	s_add_i32 s4, s84, -1
	s_xor_b32 s4, s4, s2
	v_or_b32_e32 v0, s4, v44
	v_cmp_eq_u32_e32 vcc, 0, v0
	s_and_saveexec_b64 s[0:1], vcc
	s_cbranch_execz .LBB0_32
	v_mov_b32_e32 v2, 0
	s_mov_b64 s[4:5], 0
	v_mov_b32_e32 v0, 0
	v_mov_b32_e32 v1, v2

; __device__ __forceinline__ unsigned cvt_pk_bf16(float lo, float hi) { unsigned r; asm volatile("v_cvt_pk_bf16_f32 %0, %1, %2" : "=v"(r) : "v"(lo), "v"(hi)); return r; }
;     __device__ __forceinline__ void operator()(const f32x4 (&acc)[2][2][4][2], const Unit& u, int wr, int wc, int fr, int fq) const {
;     ...
;         const float* mp = mod + (size_t)((u.pm * BM) >> 11) * 6144;
;         f32x4 g1v[2][2], csv[2][2];
; #pragma unroll
;         for (int bj = 0; bj < 2; ++bj)
; #pragma unroll
;             for (int n = 0; n < 2; ++n) { const int c = col0 + bj * HALF + 4 * n; g1v[bj][n] = *(const f32x4*)(mp + 2048 + c); csv[bj][n] = *(const f32x4*)(ng + c) * (*(const f32x4*)(mp + 4096 + c) + 1.0f); }
; #pragma unroll
;         for (int ai = 0; ai < 2; ++ai)
; #pragma unroll
;             for (int m = 0; m < 4; ++m) { const int r = row0 + ai * HALF + m * 16; float ss = 0.f;
; #pragma unroll
;                 for (int bj = 0; bj < 2; ++bj) { const int c = col0 + bj * HALF;
;                     const f32x4 xa = *(const f32x4*)(x + (size_t)r * 1024 + c), xb = *(const f32x4*)(x + (size_t)r * 1024 + c + 4);
;                     const f32x4 v0 = xa + g1v[bj][0] * acc[ai][bj][m][0], v1 = xb + g1v[bj][1] * acc[ai][bj][m][1];
;                     *(f32x4*)(out + (size_t)r * 1024 + c) = v0; *(f32x4*)(out + (size_t)r * 1024 + c + 4) = v1;
;                     ss += (v0[0] * v0[0] + v0[1] * v0[1]) + (v0[2] * v0[2] + v0[3] * v0[3]) + (v1[0] * v1[0] + v1[1] * v1[1]) + (v1[2] * v1[2] + v1[3] * v1[3]);
;                     const f32x4 a0 = v0 * csv[bj][0], a1 = v1 * csv[bj][1];
;                     u32x4 w; w.x = cvt_pk_bf16(a0[0], a0[1]); w.y = cvt_pk_bf16(a0[2], a0[3]); w.z = cvt_pk_bf16(a1[0], a1[1]); w.w = cvt_pk_bf16(a1[2], a1[3]);
;                     *(u32x4*)(a3 + (size_t)r * 1024 + c) = w; }
;                 ss += __shfl_xor(ss, 16); ss += __shfl_xor(ss, 32);
;                 if (fq == 0) rs[(size_t)r * 16 + (u.pn & 3) * 4 + wc] = ss; }
.LBB0_548:
	s_ashr_i32 s27, s38, 3
	s_mul_hi_i32 s29, s27, 0x6000
	s_mulk_i32 s27, 0x6000
	s_add_u32 s27, s86, s27
	s_addc_u32 s29, s87, s29
	v_lshl_add_u32 v164, s38, 8, v175
	v_lshl_or_b32 v160, s0, 8, v177
	s_add_u32 s40, s27, 0x2000
	v_ashrrev_i32_e32 v165, 31, v164
	s_addc_u32 s41, s29, 0
	v_ashrrev_i32_e32 v161, 31, v160
	v_lshlrev_b64 v[88:89], 12, v[164:165]
	v_lshlrev_b64 v[162:163], 2, v[160:161]
	v_lshl_add_u64 v[74:75], s[52:53], 0, v[88:89]
	s_add_u32 s38, s27, 0x4000
	v_lshl_add_u64 v[72:73], s[40:41], 0, v[162:163]
	v_lshl_add_u64 v[216:217], v[74:75], 0, v[162:163]
	s_addc_u32 s39, s29, 0
	global_load_dwordx4 v[166:169], v[216:217], off
	global_load_dwordx4 v[76:79], v[72:73], off
	s_nop 0
	global_load_dwordx4 v[72:75], v[72:73], off offset:16
	s_nop 0
	global_load_dwordx4 v[170:173], v[216:217], off offset:16
	v_lshl_add_u64 v[90:91], s[38:39], 0, v[162:163]
	global_load_dwordx4 v[182:185], v[90:91], off
	global_load_dwordx4 v[186:189], v[90:91], off offset:16
	v_lshl_add_u64 v[90:91], s[36:37], 0, v[162:163]
	global_load_dwordx4 v[190:193], v[90:91], off
	global_load_dwordx4 v[194:197], v[90:91], off offset:16
	v_or_b32_e32 v92, 0x80, v160
	v_or_b32_e32 v94, 0x84, v160
	v_ashrrev_i32_e32 v93, 31, v92
	v_lshlrev_b64 v[198:199], 11, v[164:165]
	v_ashrrev_i32_e32 v95, 31, v94
	v_lshlrev_b64 v[92:93], 2, v[92:93]
	v_lshl_add_u64 v[88:89], s[48:49], 0, v[88:89]
	v_lshl_add_u64 v[206:207], s[10:11], 0, v[198:199]
	global_load_dwordx4 v[198:201], v[90:91], off offset:528
	global_load_dwordx4 v[202:205], v[90:91], off offset:512
	v_lshl_add_u64 v[218:219], v[88:89], 0, v[162:163]
	v_lshl_add_u64 v[220:221], v[160:161], 1, v[206:207]
	v_lshl_add_u64 v[88:89], s[40:41], 0, v[92:93]
	v_lshl_add_u64 v[90:91], v[94:95], 2, s[40:41]
	v_lshl_add_u64 v[210:211], s[38:39], 0, v[92:93]
	global_load_dwordx4 v[92:95], v[88:89], off
	global_load_dwordx4 v[206:209], v[210:211], off
	s_nop 0
	global_load_dwordx4 v[210:213], v[210:211], off offset:16
	s_nop 0
	global_load_dwordx4 v[88:91], v[90:91], off
	s_lshl_b32 s0, s0, 2
	s_and_b32 s27, s0, 12
	v_lshl_add_u32 v176, v164, 12, v162
	v_add_u32_e32 v178, 0x0, v176
	global_load_dwordx4 v[228:231], v178, s[52:53] offset:512
	global_load_dwordx4 v[232:235], v178, s[52:53] offset:528
	v_add_u32_e32 v178, 0x10000, v176
	global_load_dwordx4 v[236:239], v178, s[52:53]
	global_load_dwordx4 v[240:243], v178, s[52:53] offset:16
	global_load_dwordx4 v[244:247], v178, s[52:53] offset:512
	global_load_dwordx4 v[248:251], v178, s[52:53] offset:528
	v_add_u32_e32 v178, 0x20000, v176
	global_load_dwordx4 v[252:255], v178, s[52:53]
	global_load_dwordx4 v[144:147], v178, s[52:53] offset:16
	global_load_dwordx4 v[148:151], v178, s[52:53] offset:512
	global_load_dwordx4 v[152:155], v178, s[52:53] offset:528
	v_add_u32_e32 v178, 0x30000, v176
	global_load_dwordx4 v[156:159], v178, s[52:53]
	global_load_dwordx4 v[224:227], v178, s[52:53] offset:16
	s_waitcnt vmcnt(12)
	v_pk_fma_f32 v[166:167], v[140:141], v[76:77], v[166:167]
	v_pk_fma_f32 v[168:169], v[142:143], v[78:79], v[168:169]
	v_pk_fma_f32 v[170:171], v[136:137], v[72:73], v[170:171]
	v_pk_add_f32 v[136:137], v[184:185], 1.0 op_sel_hi:[1,0]
	v_pk_add_f32 v[140:141], v[182:183], 1.0 op_sel_hi:[1,0]
	v_pk_fma_f32 v[172:173], v[138:139], v[74:75], v[172:173]
	v_pk_add_f32 v[182:183], v[188:189], 1.0 op_sel_hi:[1,0]
	v_pk_add_f32 v[184:185], v[186:187], 1.0 op_sel_hi:[1,0]
	v_pk_mul_f32 v[138:139], v[192:193], v[136:137]
	v_pk_mul_f32 v[142:143], v[190:191], v[140:141]
	v_pk_mul_f32 v[136:137], v[196:197], v[182:183]
	v_pk_mul_f32 v[140:141], v[194:195], v[184:185]
	v_pk_mul_f32 v[184:185], v[138:139], v[168:169]
	v_pk_mul_f32 v[182:183], v[142:143], v[166:167]
	global_store_dwordx4 v[218:219], v[166:169], off
	global_store_dwordx4 v[218:219], v[170:173], off offset:16
	v_pk_mul_f32 v[186:187], v[136:137], v[172:173]
	v_pk_mul_f32 v[188:189], v[140:141], v[170:171]
	v_cvt_pk_bf16_f32 v182, v182, v183
	v_cvt_pk_bf16_f32 v183, v184, v185
	v_xor_b32_e32 v192, 32, v181
	v_cvt_pk_bf16_f32 v184, v188, v189
	v_cvt_pk_bf16_f32 v185, v186, v187
	global_store_dwordx4 v[220:221], v[182:185], off
	s_nop 0
	s_nop 0
	v_and_b32_e32 v183, 64, v181
	v_xor_b32_e32 v182, 16, v181
	v_add_u32_e32 v183, 64, v183
	v_cmp_lt_i32_e32 vcc, v182, v183
	v_mul_f32_e32 v215, v167, v167
	v_mul_f32_e32 v216, v169, v169
	v_cndmask_b32_e32 v182, v181, v182, vcc
	v_cmp_lt_i32_e32 vcc, v192, v183
	v_mul_f32_e32 v222, v173, v173
	v_mul_f32_e32 v217, v171, v171
	v_cndmask_b32_e32 v183, v181, v192, vcc
	v_pk_add_f32 v[192:193], v[208:209], 1.0 op_sel_hi:[1,0]
	v_fmac_f32_e32 v215, v166, v166
	v_fmac_f32_e32 v216, v168, v168
	v_fmac_f32_e32 v222, v172, v172
	v_pk_mul_f32 v[172:173], v[204:205], v[192:193]
	v_fmac_f32_e32 v217, v170, v170
	v_add_f32_e32 v192, v215, v216
	v_add_f32_e32 v192, v192, v217
	v_add_f32_e32 v192, v222, v192
	v_lshlrev_b32_e32 v182, 2, v182
	v_pk_add_f32 v[194:195], v[206:207], 1.0 op_sel_hi:[1,0]
	v_pk_add_f32 v[196:197], v[212:213], 1.0 op_sel_hi:[1,0]
	v_pk_add_f32 v[206:207], v[210:211], 1.0 op_sel_hi:[1,0]
	v_pk_mul_f32 v[166:167], v[200:201], v[196:197]
	v_pk_mul_f32 v[168:169], v[198:199], v[206:207]
	v_pk_mul_f32 v[170:171], v[202:203], v[194:195]
	s_waitcnt vmcnt(11)
	v_pk_fma_f32 v[134:135], v[134:135], v[94:95], v[230:231]
	v_pk_fma_f32 v[132:133], v[132:133], v[92:93], v[228:229]
	s_waitcnt vmcnt(10)
	v_pk_fma_f32 v[128:129], v[128:129], v[88:89], v[232:233]
	v_mul_f32_e32 v186, v133, v133
	v_mul_f32_e32 v187, v135, v135
	v_pk_fma_f32 v[130:131], v[130:131], v[90:91], v[234:235]
	v_add_u32_e32 v178, 0x30000, v176
	global_load_dwordx4 v[228:231], v178, s[52:53] offset:512
	global_load_dwordx4 v[232:235], v178, s[52:53] offset:528
	v_mul_f32_e32 v188, v129, v129
	v_fmac_f32_e32 v186, v132, v132
	v_fmac_f32_e32 v187, v134, v134
	global_store_dwordx4 v[218:219], v[132:135], off offset:512
	global_store_dwordx4 v[218:219], v[128:131], off offset:528
	v_mul_f32_e32 v189, v131, v131
	v_pk_mul_f32 v[184:185], v[172:173], v[134:135]
	v_fmac_f32_e32 v188, v128, v128
	v_add_f32_e32 v134, v186, v187
	v_fmac_f32_e32 v189, v130, v130
	v_add_f32_e32 v134, v134, v188
	v_add_f32_e32 v134, v189, v134
	v_add_f32_e32 v188, v192, v134
	ds_bpermute_b32 v189, v182, v188
	v_pk_mul_f32 v[186:187], v[166:167], v[130:131]
	v_pk_mul_f32 v[134:135], v[168:169], v[128:129]
	v_lshlrev_b32_e32 v130, 2, v183
	v_pk_mul_f32 v[132:133], v[170:171], v[132:133]
	s_waitcnt lgkmcnt(0)
	v_add_f32_e32 v128, v188, v189
	ds_bpermute_b32 v129, v130, v128
	v_cvt_pk_bf16_f32 v132, v132, v133
	v_cvt_pk_bf16_f32 v133, v184, v185
	v_cvt_pk_bf16_f32 v134, v134, v135
	v_cvt_pk_bf16_f32 v135, v186, v187
	global_store_dwordx4 v[220:221], v[132:135], off offset:256
	s_and_saveexec_b64 s[38:39], s[6:7]
	s_cbranch_execz .LBB0_550
; __device__ __forceinline__ unsigned cvt_pk_bf16(float lo, float hi) { unsigned r; asm volatile("v_cvt_pk_bf16_f32 %0, %1, %2" : "=v"(r) : "v"(lo), "v"(hi)); return r; }
;     __device__ __forceinline__ void operator()(const f32x4 (&acc)[2][2][4][2], const Unit& u, int wr, int wc, int fr, int fq) const {
;     ...
;             for (int m = 0; m < 4; ++m) { const int r = row0 + ai * HALF + m * 16; float ss = 0.f;
; #pragma unroll
;                 for (int bj = 0; bj < 2; ++bj) { const int c = col0 + bj * HALF;
;                     const f32x4 xa = *(const f32x4*)(x + (size_t)r * 1024 + c), xb = *(const f32x4*)(x + (size_t)r * 1024 + c + 4);
;                     const f32x4 v0 = xa + g1v[bj][0] * acc[ai][bj][m][0], v1 = xb + g1v[bj][1] * acc[ai][bj][m][1];
;                     *(f32x4*)(out + (size_t)r * 1024 + c) = v0; *(f32x4*)(out + (size_t)r * 1024 + c + 4) = v1;
;                     ss += (v0[0] * v0[0] + v0[1] * v0[1]) + (v0[2] * v0[2] + v0[3] * v0[3]) + (v1[0] * v1[0] + v1[1] * v1[1]) + (v1[2] * v1[2] + v1[3] * v1[3]);
;                     const f32x4 a0 = v0 * csv[bj][0], a1 = v1 * csv[bj][1];
;                     u32x4 w; w.x = cvt_pk_bf16(a0[0], a0[1]); w.y = cvt_pk_bf16(a0[2], a0[3]); w.z = cvt_pk_bf16(a1[0], a1[1]); w.w = cvt_pk_bf16(a1[2], a1[3]);
;                     *(u32x4*)(a3 + (size_t)r * 1024 + c) = w; }
;                 ss += __shfl_xor(ss, 16); ss += __shfl_xor(ss, 32);
;                 if (fq == 0) rs[(size_t)r * 16 + (u.pn & 3) * 4 + wc] = ss; }
	v_lshlrev_b64 v[132:133], 6, v[164:165]
	v_lshl_add_u64 v[132:133], s[12:13], 0, v[132:133]
	s_lshl_b32 s0, s27, 2
	v_lshl_add_u64 v[132:133], v[132:133], 0, s[0:1]
	s_lshl_b32 s0, s64, 2
	v_lshl_add_u64 v[132:133], v[132:133], 0, s[0:1]
	s_waitcnt lgkmcnt(0)
	v_add_f32_e32 v128, v128, v129
	global_store_dword v[132:133], v128, off
.LBB0_550:
	s_or_b64 exec, exec, s[38:39]
	v_or_b32_e32 v128, 16, v164
	s_waitcnt lgkmcnt(0)
	v_ashrrev_i32_e32 v129, 31, v128
	v_lshlrev_b64 v[188:189], 12, v[128:129]
	v_lshl_add_u64 v[132:133], s[52:53], 0, v[188:189]
	v_lshl_add_u64 v[190:191], v[132:133], 0, v[162:163]
	s_nop 0
	s_nop 0
	v_lshlrev_b64 v[192:193], 11, v[128:129]
	v_lshl_add_u64 v[188:189], s[48:49], 0, v[188:189]
	v_lshl_add_u64 v[192:193], s[10:11], 0, v[192:193]
	v_lshl_add_u64 v[188:189], v[188:189], 0, v[162:163]
	v_lshl_add_u64 v[192:193], v[160:161], 1, v[192:193]
	s_waitcnt vmcnt(11)
	v_pk_fma_f32 v[126:127], v[126:127], v[78:79], v[238:239]
	v_pk_fma_f32 v[124:125], v[124:125], v[76:77], v[236:237]
	s_waitcnt vmcnt(10)
	v_pk_fma_f32 v[122:123], v[122:123], v[74:75], v[242:243]
	v_pk_fma_f32 v[120:121], v[120:121], v[72:73], v[240:241]
	v_pk_mul_f32 v[134:135], v[138:139], v[126:127]
	v_pk_mul_f32 v[132:133], v[142:143], v[124:125]
	global_store_dwordx4 v[188:189], v[124:127], off
	global_store_dwordx4 v[188:189], v[120:123], off offset:16
	v_pk_mul_f32 v[184:185], v[136:137], v[122:123]
	v_pk_mul_f32 v[186:187], v[140:141], v[120:121]
	v_cvt_pk_bf16_f32 v132, v132, v133
	v_cvt_pk_bf16_f32 v133, v134, v135
	v_mul_f32_e32 v125, v125, v125
	v_cvt_pk_bf16_f32 v134, v186, v187
	v_cvt_pk_bf16_f32 v135, v184, v185
	global_store_dwordx4 v[192:193], v[132:135], off
	s_nop 0
	s_nop 0
	v_mul_f32_e32 v127, v127, v127
	v_mul_f32_e32 v121, v121, v121
	v_fmac_f32_e32 v125, v124, v124
	v_fmac_f32_e32 v127, v126, v126
	v_mul_f32_e32 v123, v123, v123
	v_fmac_f32_e32 v121, v120, v120
	v_add_f32_e32 v120, v125, v127
	v_fmac_f32_e32 v123, v122, v122
	v_add_f32_e32 v120, v120, v121
	v_add_f32_e32 v120, v123, v120
	s_waitcnt vmcnt(9)
	v_pk_fma_f32 v[118:119], v[118:119], v[94:95], v[246:247]
	v_pk_fma_f32 v[116:117], v[116:117], v[92:93], v[244:245]
	s_waitcnt vmcnt(8)
	v_pk_fma_f32 v[112:113], v[112:113], v[88:89], v[248:249]
	v_mul_f32_e32 v121, v117, v117
	v_mul_f32_e32 v122, v119, v119
	v_pk_fma_f32 v[114:115], v[114:115], v[90:91], v[250:251]
	v_add_u32_e32 v178, 0x80000, v176
	global_load_dwordx4 v[236:239], v178, s[52:53]
	global_load_dwordx4 v[240:243], v178, s[52:53] offset:16
	global_load_dwordx4 v[244:247], v178, s[52:53] offset:512
	global_load_dwordx4 v[248:251], v178, s[52:53] offset:528
	v_mul_f32_e32 v123, v113, v113
	v_fmac_f32_e32 v121, v116, v116
	v_fmac_f32_e32 v122, v118, v118
	v_mul_f32_e32 v124, v115, v115
	v_fmac_f32_e32 v123, v112, v112
	v_add_f32_e32 v121, v121, v122
	v_fmac_f32_e32 v124, v114, v114
	v_add_f32_e32 v121, v121, v123
	v_add_f32_e32 v121, v124, v121
	v_add_f32_e32 v124, v120, v121
	ds_bpermute_b32 v125, v182, v124
	global_store_dwordx4 v[188:189], v[116:119], off offset:512
	global_store_dwordx4 v[188:189], v[112:115], off offset:528
	v_pk_mul_f32 v[122:123], v[168:169], v[112:113]
	v_pk_mul_f32 v[116:117], v[170:171], v[116:117]
	v_pk_mul_f32 v[118:119], v[172:173], v[118:119]
	s_waitcnt lgkmcnt(0)
	v_add_f32_e32 v112, v124, v125
	ds_bpermute_b32 v113, v130, v112
	v_pk_mul_f32 v[120:121], v[166:167], v[114:115]
	v_cvt_pk_bf16_f32 v114, v116, v117
	v_cvt_pk_bf16_f32 v115, v118, v119
	v_cvt_pk_bf16_f32 v116, v122, v123
	s_nop 0
	v_cvt_pk_bf16_f32 v117, v120, v121
	global_store_dwordx4 v[192:193], v[114:117], off offset:256
	s_and_saveexec_b64 s[38:39], s[6:7]
	s_cbranch_execz .LBB0_552
	v_lshlrev_b64 v[114:115], 6, v[128:129]
	v_lshl_add_u64 v[114:115], s[12:13], 0, v[114:115]
	s_lshl_b32 s0, s27, 2
	v_lshl_add_u64 v[114:115], v[114:115], 0, s[0:1]
	s_lshl_b32 s0, s64, 2
	v_lshl_add_u64 v[114:115], v[114:115], 0, s[0:1]
	s_waitcnt lgkmcnt(0)
	v_add_f32_e32 v112, v112, v113
	global_store_dword v[114:115], v112, off
.LBB0_552:
	s_or_b64 exec, exec, s[38:39]
	v_or_b32_e32 v112, 32, v164
	s_waitcnt lgkmcnt(0)
	v_ashrrev_i32_e32 v113, 31, v112
	v_lshlrev_b64 v[122:123], 12, v[112:113]
	v_lshl_add_u64 v[114:115], s[52:53], 0, v[122:123]
	v_lshl_add_u64 v[124:125], v[114:115], 0, v[162:163]
	s_nop 0
	s_nop 0
	v_lshlrev_b64 v[126:127], 11, v[112:113]
	v_lshl_add_u64 v[122:123], s[48:49], 0, v[122:123]
	v_lshl_add_u64 v[126:127], s[10:11], 0, v[126:127]
	v_lshl_add_u64 v[122:123], v[122:123], 0, v[162:163]
	v_lshl_add_u64 v[126:127], v[160:161], 1, v[126:127]
	s_waitcnt vmcnt(11)
	v_pk_fma_f32 v[110:111], v[110:111], v[78:79], v[254:255]
	v_pk_fma_f32 v[108:109], v[108:109], v[76:77], v[252:253]
	s_waitcnt vmcnt(10)
	v_pk_fma_f32 v[106:107], v[106:107], v[74:75], v[146:147]
	v_pk_fma_f32 v[104:105], v[104:105], v[72:73], v[144:145]
	v_pk_mul_f32 v[116:117], v[138:139], v[110:111]
	v_pk_mul_f32 v[114:115], v[142:143], v[108:109]
	global_store_dwordx4 v[122:123], v[108:111], off
	global_store_dwordx4 v[122:123], v[104:107], off offset:16
	v_pk_mul_f32 v[118:119], v[136:137], v[106:107]
	v_pk_mul_f32 v[120:121], v[140:141], v[104:105]
	v_cvt_pk_bf16_f32 v114, v114, v115
	v_cvt_pk_bf16_f32 v115, v116, v117
	v_mul_f32_e32 v109, v109, v109
	v_cvt_pk_bf16_f32 v116, v120, v121
	v_cvt_pk_bf16_f32 v117, v118, v119
	global_store_dwordx4 v[126:127], v[114:117], off
	s_nop 0
	s_nop 0
	v_mul_f32_e32 v111, v111, v111
	v_mul_f32_e32 v105, v105, v105
	v_fmac_f32_e32 v109, v108, v108
	v_fmac_f32_e32 v111, v110, v110
	v_mul_f32_e32 v107, v107, v107
	v_fmac_f32_e32 v105, v104, v104
	v_add_f32_e32 v104, v109, v111
	v_fmac_f32_e32 v107, v106, v106
	v_add_f32_e32 v104, v104, v105
	v_add_f32_e32 v104, v107, v104
	s_waitcnt vmcnt(9)
; __device__ __forceinline__ unsigned cvt_pk_bf16(float lo, float hi) { unsigned r; asm volatile("v_cvt_pk_bf16_f32 %0, %1, %2" : "=v"(r) : "v"(lo), "v"(hi)); return r; }
;     __device__ __forceinline__ void operator()(const f32x4 (&acc)[2][2][4][2], const Unit& u, int wr, int wc, int fr, int fq) const {
;     ...
;             for (int m = 0; m < 4; ++m) { const int r = row0 + ai * HALF + m * 16; float ss = 0.f;
; #pragma unroll
;                 for (int bj = 0; bj < 2; ++bj) { const int c = col0 + bj * HALF;
;                     const f32x4 xa = *(const f32x4*)(x + (size_t)r * 1024 + c), xb = *(const f32x4*)(x + (size_t)r * 1024 + c + 4);
;                     const f32x4 v0 = xa + g1v[bj][0] * acc[ai][bj][m][0], v1 = xb + g1v[bj][1] * acc[ai][bj][m][1];
;                     *(f32x4*)(out + (size_t)r * 1024 + c) = v0; *(f32x4*)(out + (size_t)r * 1024 + c + 4) = v1;
;                     ss += (v0[0] * v0[0] + v0[1] * v0[1]) + (v0[2] * v0[2] + v0[3] * v0[3]) + (v1[0] * v1[0] + v1[1] * v1[1]) + (v1[2] * v1[2] + v1[3] * v1[3]);
;                     const f32x4 a0 = v0 * csv[bj][0], a1 = v1 * csv[bj][1];
;                     u32x4 w; w.x = cvt_pk_bf16(a0[0], a0[1]); w.y = cvt_pk_bf16(a0[2], a0[3]); w.z = cvt_pk_bf16(a1[0], a1[1]); w.w = cvt_pk_bf16(a1[2], a1[3]);
;                     *(u32x4*)(a3 + (size_t)r * 1024 + c) = w; }
;                 ss += __shfl_xor(ss, 16); ss += __shfl_xor(ss, 32);
;                 if (fq == 0) rs[(size_t)r * 16 + (u.pn & 3) * 4 + wc] = ss; }
	v_pk_fma_f32 v[102:103], v[102:103], v[94:95], v[150:151]
	v_pk_fma_f32 v[100:101], v[100:101], v[92:93], v[148:149]
	s_waitcnt vmcnt(8)
	v_pk_fma_f32 v[96:97], v[96:97], v[88:89], v[152:153]
	v_mul_f32_e32 v105, v101, v101
	v_mul_f32_e32 v106, v103, v103
	v_pk_fma_f32 v[98:99], v[98:99], v[90:91], v[154:155]
	v_add_u32_e32 v178, 0x90000, v176
	global_load_dwordx4 v[252:255], v178, s[52:53]
	global_load_dwordx4 v[144:147], v178, s[52:53] offset:16
	global_load_dwordx4 v[148:151], v178, s[52:53] offset:512
	global_load_dwordx4 v[152:155], v178, s[52:53] offset:528
	v_mul_f32_e32 v107, v97, v97
	v_fmac_f32_e32 v105, v100, v100
	v_fmac_f32_e32 v106, v102, v102
	v_mul_f32_e32 v108, v99, v99
	v_fmac_f32_e32 v107, v96, v96
	v_add_f32_e32 v105, v105, v106
	v_fmac_f32_e32 v108, v98, v98
	v_add_f32_e32 v105, v105, v107
	v_add_f32_e32 v105, v108, v105
	v_add_f32_e32 v108, v104, v105
	ds_bpermute_b32 v109, v182, v108
	global_store_dwordx4 v[122:123], v[100:103], off offset:512
	global_store_dwordx4 v[122:123], v[96:99], off offset:528
	v_pk_mul_f32 v[106:107], v[168:169], v[96:97]
	v_pk_mul_f32 v[100:101], v[170:171], v[100:101]
	v_pk_mul_f32 v[102:103], v[172:173], v[102:103]
	s_waitcnt lgkmcnt(0)
	v_add_f32_e32 v96, v108, v109
	ds_bpermute_b32 v97, v130, v96
	v_pk_mul_f32 v[104:105], v[166:167], v[98:99]
	v_cvt_pk_bf16_f32 v98, v100, v101
	v_cvt_pk_bf16_f32 v99, v102, v103
	v_cvt_pk_bf16_f32 v100, v106, v107
	s_nop 0
	v_cvt_pk_bf16_f32 v101, v104, v105
	global_store_dwordx4 v[126:127], v[98:101], off offset:256
	s_and_saveexec_b64 s[38:39], s[6:7]
	s_cbranch_execz .LBB0_554
	v_lshlrev_b64 v[98:99], 6, v[112:113]
	v_lshl_add_u64 v[98:99], s[12:13], 0, v[98:99]
	s_lshl_b32 s0, s27, 2
	v_lshl_add_u64 v[98:99], v[98:99], 0, s[0:1]
	s_lshl_b32 s0, s64, 2
	v_lshl_add_u64 v[98:99], v[98:99], 0, s[0:1]
	s_waitcnt lgkmcnt(0)
	v_add_f32_e32 v96, v96, v97
	global_store_dword v[98:99], v96, off
.LBB0_554:
	s_or_b64 exec, exec, s[38:39]
	v_or_b32_e32 v96, 48, v164
	s_waitcnt lgkmcnt(0)
	v_ashrrev_i32_e32 v97, 31, v96
	v_lshlrev_b64 v[106:107], 12, v[96:97]
	v_lshl_add_u64 v[98:99], s[52:53], 0, v[106:107]
	v_lshl_add_u64 v[108:109], v[98:99], 0, v[162:163]
	s_nop 0
	s_nop 0
	v_lshlrev_b64 v[110:111], 11, v[96:97]
	v_lshl_add_u64 v[106:107], s[48:49], 0, v[106:107]
	v_lshl_add_u64 v[110:111], s[10:11], 0, v[110:111]
	v_lshl_add_u64 v[106:107], v[106:107], 0, v[162:163]
	v_lshl_add_u64 v[110:111], v[160:161], 1, v[110:111]
	s_waitcnt vmcnt(11)
	v_pk_fma_f32 v[86:87], v[86:87], v[78:79], v[158:159]
	v_pk_fma_f32 v[84:85], v[84:85], v[76:77], v[156:157]
	s_waitcnt vmcnt(10)
	v_pk_fma_f32 v[82:83], v[82:83], v[74:75], v[226:227]
	v_pk_fma_f32 v[80:81], v[80:81], v[72:73], v[224:225]
	v_pk_mul_f32 v[100:101], v[138:139], v[86:87]
	v_pk_mul_f32 v[98:99], v[142:143], v[84:85]
	global_store_dwordx4 v[106:107], v[84:87], off
	global_store_dwordx4 v[106:107], v[80:83], off offset:16
	v_pk_mul_f32 v[102:103], v[136:137], v[82:83]
	v_pk_mul_f32 v[104:105], v[140:141], v[80:81]
	v_cvt_pk_bf16_f32 v98, v98, v99
	v_cvt_pk_bf16_f32 v99, v100, v101
	v_mul_f32_e32 v85, v85, v85
	v_cvt_pk_bf16_f32 v100, v104, v105
	v_cvt_pk_bf16_f32 v101, v102, v103
	global_store_dwordx4 v[110:111], v[98:101], off
	s_nop 0
	s_nop 0
	v_mul_f32_e32 v87, v87, v87
	v_mul_f32_e32 v81, v81, v81
	v_fmac_f32_e32 v85, v84, v84
	v_fmac_f32_e32 v87, v86, v86
	v_mul_f32_e32 v83, v83, v83
	v_fmac_f32_e32 v81, v80, v80
	v_add_f32_e32 v80, v85, v87
	v_fmac_f32_e32 v83, v82, v82
	v_add_f32_e32 v80, v80, v81
	v_add_f32_e32 v80, v83, v80
	s_waitcnt vmcnt(9)
	v_pk_fma_f32 v[70:71], v[70:71], v[94:95], v[230:231]
	v_pk_fma_f32 v[68:69], v[68:69], v[92:93], v[228:229]
	s_waitcnt vmcnt(8)
	v_pk_fma_f32 v[64:65], v[64:65], v[88:89], v[232:233]
	v_mul_f32_e32 v81, v69, v69
	v_mul_f32_e32 v82, v71, v71
	v_pk_fma_f32 v[66:67], v[66:67], v[90:91], v[234:235]
	v_add_u32_e32 v178, 0xa0000, v176
	global_load_dwordx4 v[156:159], v178, s[52:53]
	global_load_dwordx4 v[224:227], v178, s[52:53] offset:16
	global_load_dwordx4 v[228:231], v178, s[52:53] offset:512
	global_load_dwordx4 v[232:235], v178, s[52:53] offset:528
	v_mul_f32_e32 v83, v65, v65
	v_fmac_f32_e32 v81, v68, v68
	v_fmac_f32_e32 v82, v70, v70
	v_mul_f32_e32 v84, v67, v67
	v_fmac_f32_e32 v83, v64, v64
	v_add_f32_e32 v81, v81, v82
	v_fmac_f32_e32 v84, v66, v66
	v_add_f32_e32 v81, v81, v83
	v_add_f32_e32 v81, v84, v81
	v_add_f32_e32 v84, v80, v81
	ds_bpermute_b32 v85, v182, v84
	global_store_dwordx4 v[106:107], v[68:71], off offset:512
	global_store_dwordx4 v[106:107], v[64:67], off offset:528
	v_pk_mul_f32 v[82:83], v[168:169], v[64:65]
	v_pk_mul_f32 v[68:69], v[170:171], v[68:69]
	v_pk_mul_f32 v[70:71], v[172:173], v[70:71]
	s_waitcnt lgkmcnt(0)
	v_add_f32_e32 v64, v84, v85
	ds_bpermute_b32 v65, v130, v64
	v_pk_mul_f32 v[80:81], v[166:167], v[66:67]
	v_cvt_pk_bf16_f32 v66, v68, v69
	v_cvt_pk_bf16_f32 v67, v70, v71
	v_cvt_pk_bf16_f32 v68, v82, v83
	s_nop 0
	v_cvt_pk_bf16_f32 v69, v80, v81
	global_store_dwordx4 v[110:111], v[66:69], off offset:256
	s_and_saveexec_b64 s[38:39], s[6:7]
	s_cbranch_execz .LBB0_556
	v_lshlrev_b64 v[66:67], 6, v[96:97]
	v_lshl_add_u64 v[66:67], s[12:13], 0, v[66:67]
	s_lshl_b32 s0, s27, 2
	v_lshl_add_u64 v[66:67], v[66:67], 0, s[0:1]
	s_lshl_b32 s0, s64, 2
	v_lshl_add_u64 v[66:67], v[66:67], 0, s[0:1]
	s_waitcnt lgkmcnt(0)
	v_add_f32_e32 v64, v64, v65
	global_store_dword v[66:67], v64, off
; __device__ __forceinline__ unsigned cvt_pk_bf16(float lo, float hi) { unsigned r; asm volatile("v_cvt_pk_bf16_f32 %0, %1, %2" : "=v"(r) : "v"(lo), "v"(hi)); return r; }
;     __device__ __forceinline__ void operator()(const f32x4 (&acc)[2][2][4][2], const Unit& u, int wr, int wc, int fr, int fq) const {
;     ...
;             for (int m = 0; m < 4; ++m) { const int r = row0 + ai * HALF + m * 16; float ss = 0.f;
; #pragma unroll
;                 for (int bj = 0; bj < 2; ++bj) { const int c = col0 + bj * HALF;
;                     const f32x4 xa = *(const f32x4*)(x + (size_t)r * 1024 + c), xb = *(const f32x4*)(x + (size_t)r * 1024 + c + 4);
;                     const f32x4 v0 = xa + g1v[bj][0] * acc[ai][bj][m][0], v1 = xb + g1v[bj][1] * acc[ai][bj][m][1];
;                     *(f32x4*)(out + (size_t)r * 1024 + c) = v0; *(f32x4*)(out + (size_t)r * 1024 + c + 4) = v1;
;                     ss += (v0[0] * v0[0] + v0[1] * v0[1]) + (v0[2] * v0[2] + v0[3] * v0[3]) + (v1[0] * v1[0] + v1[1] * v1[1]) + (v1[2] * v1[2] + v1[3] * v1[3]);
;                     const f32x4 a0 = v0 * csv[bj][0], a1 = v1 * csv[bj][1];
;                     u32x4 w; w.x = cvt_pk_bf16(a0[0], a0[1]); w.y = cvt_pk_bf16(a0[2], a0[3]); w.z = cvt_pk_bf16(a1[0], a1[1]); w.w = cvt_pk_bf16(a1[2], a1[3]);
;                     *(u32x4*)(a3 + (size_t)r * 1024 + c) = w; }
;                 ss += __shfl_xor(ss, 16); ss += __shfl_xor(ss, 32);
;                 if (fq == 0) rs[(size_t)r * 16 + (u.pn & 3) * 4 + wc] = ss; }
.LBB0_556:
	s_or_b64 exec, exec, s[38:39]
	v_add_u32_e32 v64, 0x80, v164
	s_waitcnt lgkmcnt(0)
	v_ashrrev_i32_e32 v65, 31, v64
	v_lshlrev_b64 v[70:71], 12, v[64:65]
	v_lshl_add_u64 v[66:67], s[52:53], 0, v[70:71]
	v_lshl_add_u64 v[84:85], v[66:67], 0, v[162:163]
	s_nop 0
	s_nop 0
	v_lshlrev_b64 v[86:87], 11, v[64:65]
	v_lshl_add_u64 v[70:71], s[48:49], 0, v[70:71]
	v_lshl_add_u64 v[86:87], s[10:11], 0, v[86:87]
	v_lshl_add_u64 v[70:71], v[70:71], 0, v[162:163]
	v_lshl_add_u64 v[86:87], v[160:161], 1, v[86:87]
	s_waitcnt vmcnt(11)
	v_pk_fma_f32 v[62:63], v[62:63], v[78:79], v[238:239]
	v_pk_fma_f32 v[60:61], v[60:61], v[76:77], v[236:237]
	s_waitcnt vmcnt(10)
	v_pk_fma_f32 v[58:59], v[58:59], v[74:75], v[242:243]
	v_pk_fma_f32 v[56:57], v[56:57], v[72:73], v[240:241]
	v_pk_mul_f32 v[68:69], v[138:139], v[62:63]
	v_pk_mul_f32 v[66:67], v[142:143], v[60:61]
	global_store_dwordx4 v[70:71], v[60:63], off
	global_store_dwordx4 v[70:71], v[56:59], off offset:16
	v_pk_mul_f32 v[80:81], v[136:137], v[58:59]
	v_pk_mul_f32 v[82:83], v[140:141], v[56:57]
	v_cvt_pk_bf16_f32 v66, v66, v67
	v_cvt_pk_bf16_f32 v67, v68, v69
	v_mul_f32_e32 v61, v61, v61
	v_cvt_pk_bf16_f32 v68, v82, v83
	v_cvt_pk_bf16_f32 v69, v80, v81
	global_store_dwordx4 v[86:87], v[66:69], off
	s_nop 0
	s_nop 0
	v_mul_f32_e32 v63, v63, v63
	v_mul_f32_e32 v57, v57, v57
	v_fmac_f32_e32 v61, v60, v60
	v_fmac_f32_e32 v63, v62, v62
	v_mul_f32_e32 v59, v59, v59
	v_fmac_f32_e32 v57, v56, v56
	v_add_f32_e32 v56, v61, v63
	v_fmac_f32_e32 v59, v58, v58
	v_add_f32_e32 v56, v56, v57
	v_add_f32_e32 v56, v59, v56
	s_waitcnt vmcnt(9)
	v_pk_fma_f32 v[54:55], v[54:55], v[94:95], v[246:247]
	v_pk_fma_f32 v[52:53], v[52:53], v[92:93], v[244:245]
	s_waitcnt vmcnt(8)
	v_pk_fma_f32 v[48:49], v[48:49], v[88:89], v[248:249]
	v_mul_f32_e32 v57, v53, v53
	v_mul_f32_e32 v58, v55, v55
	v_pk_fma_f32 v[50:51], v[50:51], v[90:91], v[250:251]
	v_add_u32_e32 v178, 0xb0000, v176
	global_load_dwordx4 v[236:239], v178, s[52:53]
	global_load_dwordx4 v[240:243], v178, s[52:53] offset:16
	global_load_dwordx4 v[244:247], v178, s[52:53] offset:512
	global_load_dwordx4 v[248:251], v178, s[52:53] offset:528
	v_mul_f32_e32 v59, v49, v49
	v_fmac_f32_e32 v57, v52, v52
	v_fmac_f32_e32 v58, v54, v54
	v_mul_f32_e32 v60, v51, v51
	v_fmac_f32_e32 v59, v48, v48
	v_add_f32_e32 v57, v57, v58
	v_fmac_f32_e32 v60, v50, v50
	v_add_f32_e32 v57, v57, v59
	v_add_f32_e32 v57, v60, v57
	v_add_f32_e32 v60, v56, v57
	ds_bpermute_b32 v61, v182, v60
	global_store_dwordx4 v[70:71], v[52:55], off offset:512
	global_store_dwordx4 v[70:71], v[48:51], off offset:528
	v_pk_mul_f32 v[58:59], v[168:169], v[48:49]
	v_pk_mul_f32 v[52:53], v[170:171], v[52:53]
	v_pk_mul_f32 v[54:55], v[172:173], v[54:55]
	s_waitcnt lgkmcnt(0)
	v_add_f32_e32 v48, v60, v61
	ds_bpermute_b32 v49, v130, v48
	v_pk_mul_f32 v[56:57], v[166:167], v[50:51]
	v_cvt_pk_bf16_f32 v50, v52, v53
	v_cvt_pk_bf16_f32 v51, v54, v55
	v_cvt_pk_bf16_f32 v52, v58, v59
	s_nop 0
	v_cvt_pk_bf16_f32 v53, v56, v57
	global_store_dwordx4 v[86:87], v[50:53], off offset:256
	s_and_saveexec_b64 s[38:39], s[6:7]
	s_cbranch_execz .LBB0_558
	v_lshlrev_b64 v[50:51], 6, v[64:65]
	v_lshl_add_u64 v[50:51], s[12:13], 0, v[50:51]
	s_lshl_b32 s0, s27, 2
	v_lshl_add_u64 v[50:51], v[50:51], 0, s[0:1]
	s_lshl_b32 s0, s64, 2
	v_lshl_add_u64 v[50:51], v[50:51], 0, s[0:1]
	s_waitcnt lgkmcnt(0)
	v_add_f32_e32 v48, v48, v49
	global_store_dword v[50:51], v48, off
.LBB0_558:
	s_or_b64 exec, exec, s[38:39]
	v_add_u32_e32 v48, 0x90, v164
	s_waitcnt lgkmcnt(0)
	v_ashrrev_i32_e32 v49, 31, v48
	v_lshlrev_b64 v[58:59], 12, v[48:49]
	v_lshl_add_u64 v[50:51], s[52:53], 0, v[58:59]
	v_lshl_add_u64 v[60:61], v[50:51], 0, v[162:163]
	s_nop 0
	s_nop 0
	v_lshlrev_b64 v[62:63], 11, v[48:49]
	v_lshl_add_u64 v[58:59], s[48:49], 0, v[58:59]
	v_lshl_add_u64 v[62:63], s[10:11], 0, v[62:63]
	v_lshl_add_u64 v[58:59], v[58:59], 0, v[162:163]
	v_lshl_add_u64 v[62:63], v[160:161], 1, v[62:63]
	s_waitcnt vmcnt(11)
	v_pk_fma_f32 v[46:47], v[46:47], v[78:79], v[254:255]
	v_pk_fma_f32 v[44:45], v[44:45], v[76:77], v[252:253]
	s_waitcnt vmcnt(10)
	v_pk_fma_f32 v[42:43], v[42:43], v[74:75], v[146:147]
	v_pk_fma_f32 v[40:41], v[40:41], v[72:73], v[144:145]
	v_pk_mul_f32 v[52:53], v[138:139], v[46:47]
	v_pk_mul_f32 v[50:51], v[142:143], v[44:45]
	global_store_dwordx4 v[58:59], v[44:47], off
	global_store_dwordx4 v[58:59], v[40:43], off offset:16
	v_pk_mul_f32 v[54:55], v[136:137], v[42:43]
	v_pk_mul_f32 v[56:57], v[140:141], v[40:41]
	v_cvt_pk_bf16_f32 v50, v50, v51
	v_cvt_pk_bf16_f32 v51, v52, v53
	v_mul_f32_e32 v45, v45, v45
	v_cvt_pk_bf16_f32 v52, v56, v57
	v_cvt_pk_bf16_f32 v53, v54, v55
	global_store_dwordx4 v[62:63], v[50:53], off
	s_nop 0
	s_nop 0
	v_mul_f32_e32 v47, v47, v47
	v_mul_f32_e32 v41, v41, v41
	v_fmac_f32_e32 v45, v44, v44
	v_fmac_f32_e32 v47, v46, v46
	v_mul_f32_e32 v43, v43, v43
	v_fmac_f32_e32 v41, v40, v40
	v_add_f32_e32 v40, v45, v47
	v_fmac_f32_e32 v43, v42, v42
	v_add_f32_e32 v40, v40, v41
	v_add_f32_e32 v40, v43, v40
	s_waitcnt vmcnt(9)
	v_pk_fma_f32 v[38:39], v[38:39], v[94:95], v[150:151]
	v_pk_fma_f32 v[36:37], v[36:37], v[92:93], v[148:149]
	s_waitcnt vmcnt(8)
	v_pk_fma_f32 v[32:33], v[32:33], v[88:89], v[152:153]
	v_mul_f32_e32 v41, v37, v37
	v_mul_f32_e32 v42, v39, v39
	v_pk_fma_f32 v[34:35], v[34:35], v[90:91], v[154:155]
	v_mul_f32_e32 v43, v33, v33
	v_fmac_f32_e32 v41, v36, v36
	v_fmac_f32_e32 v42, v38, v38
	v_mul_f32_e32 v44, v35, v35
	v_fmac_f32_e32 v43, v32, v32
	v_add_f32_e32 v41, v41, v42
	v_fmac_f32_e32 v44, v34, v34
	v_add_f32_e32 v41, v41, v43
	v_add_f32_e32 v41, v44, v41
	v_add_f32_e32 v44, v40, v41
	ds_bpermute_b32 v45, v182, v44
	global_store_dwordx4 v[58:59], v[36:39], off offset:512
	global_store_dwordx4 v[58:59], v[32:35], off offset:528
	v_pk_mul_f32 v[42:43], v[168:169], v[32:33]
	v_pk_mul_f32 v[36:37], v[170:171], v[36:37]
	v_pk_mul_f32 v[38:39], v[172:173], v[38:39]
	s_waitcnt lgkmcnt(0)
	v_add_f32_e32 v32, v44, v45
	ds_bpermute_b32 v33, v130, v32
	v_pk_mul_f32 v[40:41], v[166:167], v[34:35]
	v_cvt_pk_bf16_f32 v34, v36, v37
	v_cvt_pk_bf16_f32 v35, v38, v39
	v_cvt_pk_bf16_f32 v36, v42, v43
	s_nop 0
	v_cvt_pk_bf16_f32 v37, v40, v41
	global_store_dwordx4 v[62:63], v[34:37], off offset:256
	s_and_saveexec_b64 s[38:39], s[6:7]
	s_cbranch_execz .LBB0_560
	v_lshlrev_b64 v[34:35], 6, v[48:49]
	v_lshl_add_u64 v[34:35], s[12:13], 0, v[34:35]
	s_lshl_b32 s0, s27, 2
	v_lshl_add_u64 v[34:35], v[34:35], 0, s[0:1]
	s_lshl_b32 s0, s64, 2
	v_lshl_add_u64 v[34:35], v[34:35], 0, s[0:1]
	s_waitcnt lgkmcnt(0)
	v_add_f32_e32 v32, v32, v33
	global_store_dword v[34:35], v32, off
; __device__ __forceinline__ unsigned cvt_pk_bf16(float lo, float hi) { unsigned r; asm volatile("v_cvt_pk_bf16_f32 %0, %1, %2" : "=v"(r) : "v"(lo), "v"(hi)); return r; }
;     __device__ __forceinline__ void operator()(const f32x4 (&acc)[2][2][4][2], const Unit& u, int wr, int wc, int fr, int fq) const {
;     ...
;             for (int m = 0; m < 4; ++m) { const int r = row0 + ai * HALF + m * 16; float ss = 0.f;
; #pragma unroll
;                 for (int bj = 0; bj < 2; ++bj) { const int c = col0 + bj * HALF;
;                     const f32x4 xa = *(const f32x4*)(x + (size_t)r * 1024 + c), xb = *(const f32x4*)(x + (size_t)r * 1024 + c + 4);
;                     const f32x4 v0 = xa + g1v[bj][0] * acc[ai][bj][m][0], v1 = xb + g1v[bj][1] * acc[ai][bj][m][1];
;                     *(f32x4*)(out + (size_t)r * 1024 + c) = v0; *(f32x4*)(out + (size_t)r * 1024 + c + 4) = v1;
;                     ss += (v0[0] * v0[0] + v0[1] * v0[1]) + (v0[2] * v0[2] + v0[3] * v0[3]) + (v1[0] * v1[0] + v1[1] * v1[1]) + (v1[2] * v1[2] + v1[3] * v1[3]);
;                     const f32x4 a0 = v0 * csv[bj][0], a1 = v1 * csv[bj][1];
;                     u32x4 w; w.x = cvt_pk_bf16(a0[0], a0[1]); w.y = cvt_pk_bf16(a0[2], a0[3]); w.z = cvt_pk_bf16(a1[0], a1[1]); w.w = cvt_pk_bf16(a1[2], a1[3]);
;                     *(u32x4*)(a3 + (size_t)r * 1024 + c) = w; }
;                 ss += __shfl_xor(ss, 16); ss += __shfl_xor(ss, 32);
;                 if (fq == 0) rs[(size_t)r * 16 + (u.pn & 3) * 4 + wc] = ss; }
.LBB0_560:
	s_or_b64 exec, exec, s[38:39]
	v_add_u32_e32 v32, 0xa0, v164
	s_waitcnt lgkmcnt(0)
	v_ashrrev_i32_e32 v33, 31, v32
	v_lshlrev_b64 v[42:43], 12, v[32:33]
	v_lshl_add_u64 v[34:35], s[52:53], 0, v[42:43]
	v_lshl_add_u64 v[44:45], v[34:35], 0, v[162:163]
	s_nop 0
	s_nop 0
	v_lshlrev_b64 v[46:47], 11, v[32:33]
	v_lshl_add_u64 v[42:43], s[48:49], 0, v[42:43]
	v_lshl_add_u64 v[46:47], s[10:11], 0, v[46:47]
	v_lshl_add_u64 v[42:43], v[42:43], 0, v[162:163]
	v_lshl_add_u64 v[46:47], v[160:161], 1, v[46:47]
	s_waitcnt vmcnt(7)
	v_pk_fma_f32 v[30:31], v[30:31], v[78:79], v[158:159]
	v_pk_fma_f32 v[28:29], v[28:29], v[76:77], v[156:157]
	s_waitcnt vmcnt(6)
	v_pk_fma_f32 v[26:27], v[26:27], v[74:75], v[226:227]
	v_pk_fma_f32 v[24:25], v[24:25], v[72:73], v[224:225]
	v_pk_mul_f32 v[36:37], v[138:139], v[30:31]
	v_pk_mul_f32 v[34:35], v[142:143], v[28:29]
	global_store_dwordx4 v[42:43], v[28:31], off
	global_store_dwordx4 v[42:43], v[24:27], off offset:16
	v_pk_mul_f32 v[38:39], v[136:137], v[26:27]
	v_pk_mul_f32 v[40:41], v[140:141], v[24:25]
	v_cvt_pk_bf16_f32 v34, v34, v35
	v_cvt_pk_bf16_f32 v35, v36, v37
	v_mul_f32_e32 v29, v29, v29
	v_cvt_pk_bf16_f32 v36, v40, v41
	v_cvt_pk_bf16_f32 v37, v38, v39
	global_store_dwordx4 v[46:47], v[34:37], off
	s_nop 0
	s_nop 0
	v_mul_f32_e32 v31, v31, v31
	v_mul_f32_e32 v25, v25, v25
	v_fmac_f32_e32 v29, v28, v28
	v_fmac_f32_e32 v31, v30, v30
	v_mul_f32_e32 v27, v27, v27
	v_fmac_f32_e32 v25, v24, v24
	v_add_f32_e32 v24, v29, v31
	v_fmac_f32_e32 v27, v26, v26
	v_add_f32_e32 v24, v24, v25
	v_add_f32_e32 v24, v27, v24
	s_waitcnt vmcnt(5)
	v_pk_fma_f32 v[22:23], v[22:23], v[94:95], v[230:231]
	v_pk_fma_f32 v[20:21], v[20:21], v[92:93], v[228:229]
	s_waitcnt vmcnt(4)
	v_pk_fma_f32 v[16:17], v[16:17], v[88:89], v[232:233]
	v_mul_f32_e32 v25, v21, v21
	v_mul_f32_e32 v26, v23, v23
	v_pk_fma_f32 v[18:19], v[18:19], v[90:91], v[234:235]
	v_mul_f32_e32 v27, v17, v17
	v_fmac_f32_e32 v25, v20, v20
	v_fmac_f32_e32 v26, v22, v22
	v_mul_f32_e32 v28, v19, v19
	v_fmac_f32_e32 v27, v16, v16
	v_add_f32_e32 v25, v25, v26
	v_fmac_f32_e32 v28, v18, v18
	v_add_f32_e32 v25, v25, v27
	v_add_f32_e32 v25, v28, v25
	v_add_f32_e32 v28, v24, v25
	ds_bpermute_b32 v29, v182, v28
	global_store_dwordx4 v[42:43], v[20:23], off offset:512
	global_store_dwordx4 v[42:43], v[16:19], off offset:528
	v_pk_mul_f32 v[26:27], v[168:169], v[16:17]
	v_pk_mul_f32 v[20:21], v[170:171], v[20:21]
	v_pk_mul_f32 v[22:23], v[172:173], v[22:23]
	s_waitcnt lgkmcnt(0)
	v_add_f32_e32 v16, v28, v29
	ds_bpermute_b32 v17, v130, v16
	v_pk_mul_f32 v[24:25], v[166:167], v[18:19]
	v_cvt_pk_bf16_f32 v18, v20, v21
	v_cvt_pk_bf16_f32 v19, v22, v23
	v_cvt_pk_bf16_f32 v20, v26, v27
	s_nop 0
	v_cvt_pk_bf16_f32 v21, v24, v25
	global_store_dwordx4 v[46:47], v[18:21], off offset:256
	s_and_saveexec_b64 s[38:39], s[6:7]
	s_cbranch_execz .LBB0_562
	v_lshlrev_b64 v[18:19], 6, v[32:33]
	v_lshl_add_u64 v[18:19], s[12:13], 0, v[18:19]
	s_lshl_b32 s0, s27, 2
	v_lshl_add_u64 v[18:19], v[18:19], 0, s[0:1]
	s_lshl_b32 s0, s64, 2
	v_lshl_add_u64 v[18:19], v[18:19], 0, s[0:1]
	s_waitcnt lgkmcnt(0)
	v_add_f32_e32 v16, v16, v17
	global_store_dword v[18:19], v16, off
.LBB0_562:
	s_or_b64 exec, exec, s[38:39]
	v_add_u32_e32 v16, 0xb0, v164
	s_waitcnt lgkmcnt(0)
	v_ashrrev_i32_e32 v17, 31, v16
	v_lshlrev_b64 v[26:27], 12, v[16:17]
	v_lshl_add_u64 v[18:19], s[52:53], 0, v[26:27]
	v_lshl_add_u64 v[28:29], v[18:19], 0, v[162:163]
	s_nop 0
	s_nop 0
	v_lshlrev_b64 v[30:31], 11, v[16:17]
	v_lshl_add_u64 v[26:27], s[48:49], 0, v[26:27]
	v_lshl_add_u64 v[30:31], s[10:11], 0, v[30:31]
	v_lshl_add_u64 v[26:27], v[26:27], 0, v[162:163]
	v_lshl_add_u64 v[30:31], v[160:161], 1, v[30:31]
	s_waitcnt vmcnt(3)
	v_pk_fma_f32 v[14:15], v[14:15], v[78:79], v[238:239]
	v_pk_fma_f32 v[12:13], v[12:13], v[76:77], v[236:237]
	s_waitcnt vmcnt(2)
	v_pk_fma_f32 v[10:11], v[10:11], v[74:75], v[242:243]
	v_pk_fma_f32 v[8:9], v[8:9], v[72:73], v[240:241]
	v_pk_mul_f32 v[20:21], v[138:139], v[14:15]
	v_pk_mul_f32 v[18:19], v[142:143], v[12:13]
	global_store_dwordx4 v[26:27], v[12:15], off
	global_store_dwordx4 v[26:27], v[8:11], off offset:16
	v_pk_mul_f32 v[22:23], v[136:137], v[10:11]
	v_pk_mul_f32 v[24:25], v[140:141], v[8:9]
	v_cvt_pk_bf16_f32 v18, v18, v19
	v_cvt_pk_bf16_f32 v19, v20, v21
	v_mul_f32_e32 v13, v13, v13
	v_cvt_pk_bf16_f32 v20, v24, v25
	v_cvt_pk_bf16_f32 v21, v22, v23
	global_store_dwordx4 v[30:31], v[18:21], off
	s_nop 0
	s_nop 0
	v_mul_f32_e32 v15, v15, v15
	v_mul_f32_e32 v9, v9, v9
	v_fmac_f32_e32 v13, v12, v12
	v_fmac_f32_e32 v15, v14, v14
	v_mul_f32_e32 v11, v11, v11
	v_fmac_f32_e32 v9, v8, v8
	v_add_f32_e32 v8, v13, v15
	v_fmac_f32_e32 v11, v10, v10
	v_add_f32_e32 v8, v8, v9
	v_add_f32_e32 v8, v11, v8
	s_waitcnt vmcnt(1)
	v_pk_fma_f32 v[6:7], v[6:7], v[94:95], v[246:247]
	v_pk_fma_f32 v[4:5], v[4:5], v[92:93], v[244:245]
	s_waitcnt vmcnt(0)
	v_pk_fma_f32 v[0:1], v[0:1], v[88:89], v[248:249]
	v_mul_f32_e32 v9, v5, v5
	v_mul_f32_e32 v10, v7, v7
	v_pk_fma_f32 v[2:3], v[2:3], v[90:91], v[250:251]
	v_mul_f32_e32 v11, v1, v1
	v_fmac_f32_e32 v9, v4, v4
	v_fmac_f32_e32 v10, v6, v6
	v_mul_f32_e32 v12, v3, v3
	v_fmac_f32_e32 v11, v0, v0
	v_add_f32_e32 v9, v9, v10
	v_fmac_f32_e32 v12, v2, v2
	v_add_f32_e32 v9, v9, v11
	v_add_f32_e32 v9, v12, v9
	v_add_f32_e32 v12, v8, v9
	ds_bpermute_b32 v13, v182, v12
	global_store_dwordx4 v[26:27], v[4:7], off offset:512
	global_store_dwordx4 v[26:27], v[0:3], off offset:528
	v_pk_mul_f32 v[10:11], v[168:169], v[0:1]
	v_pk_mul_f32 v[4:5], v[170:171], v[4:5]
	v_pk_mul_f32 v[6:7], v[172:173], v[6:7]
	s_waitcnt lgkmcnt(0)
	v_add_f32_e32 v0, v12, v13
	ds_bpermute_b32 v1, v130, v0
	v_pk_mul_f32 v[8:9], v[166:167], v[2:3]
	v_cvt_pk_bf16_f32 v2, v4, v5
	v_cvt_pk_bf16_f32 v3, v6, v7
	v_cvt_pk_bf16_f32 v4, v10, v11
	s_nop 0
	v_cvt_pk_bf16_f32 v5, v8, v9
	global_store_dwordx4 v[30:31], v[2:5], off offset:256
	s_and_saveexec_b64 s[38:39], s[6:7]
	s_cbranch_execz .LBB0_564
	v_lshlrev_b64 v[2:3], 6, v[16:17]
	v_lshl_add_u64 v[2:3], s[12:13], 0, v[2:3]
	s_lshl_b32 s0, s27, 2
	v_lshl_add_u64 v[2:3], v[2:3], 0, s[0:1]
	s_lshl_b32 s0, s64, 2
	v_lshl_add_u64 v[2:3], v[2:3], 0, s[0:1]
	s_waitcnt lgkmcnt(0)
	v_add_f32_e32 v0, v0, v1
	global_store_dword v[2:3], v0, off

; __global__ void __launch_bounds__(512, 2) mega_fwd(Args A) {
	.amdhsa_kernel _Z8mega_fwd4Args
		.amdhsa_group_segment_fixed_size 0
		.amdhsa_private_segment_fixed_size 0
		.amdhsa_kernarg_size 448
		.amdhsa_user_sgpr_count 2
		.amdhsa_user_sgpr_dispatch_ptr 0
		.amdhsa_user_sgpr_queue_ptr 0
		.amdhsa_user_sgpr_kernarg_segment_ptr 1
		.amdhsa_user_sgpr_dispatch_id 0
		.amdhsa_user_sgpr_kernarg_preload_length 0
		.amdhsa_user_sgpr_kernarg_preload_offset 0
		.amdhsa_user_sgpr_private_segment_size 0
		.amdhsa_uses_dynamic_stack 0
		.amdhsa_enable_private_segment 0
		.amdhsa_system_sgpr_workgroup_id_x 1
		.amdhsa_system_sgpr_workgroup_id_y 0
		.amdhsa_system_sgpr_workgroup_id_z 0
		.amdhsa_system_sgpr_workgroup_info 0
		.amdhsa_system_vgpr_workitem_id 2
		.amdhsa_next_free_vgpr 256
		.amdhsa_next_free_sgpr 98
		.amdhsa_accum_offset 256
		.amdhsa_reserve_vcc 1
		.amdhsa_float_round_mode_32 0
		.amdhsa_float_round_mode_16_64 0
		.amdhsa_float_denorm_mode_32 3
		.amdhsa_float_denorm_mode_16_64 3
		.amdhsa_dx10_clamp 1
		.amdhsa_ieee_mode 1
		.amdhsa_fp16_overflow 0
		.amdhsa_tg_split 0
		.amdhsa_exception_fp_ieee_invalid_op 0
		.amdhsa_exception_fp_denorm_src 0
		.amdhsa_exception_fp_ieee_div_zero 0
		.amdhsa_exception_fp_ieee_overflow 0
		.amdhsa_exception_fp_ieee_underflow 0
		.amdhsa_exception_fp_ieee_inexact 0
		.amdhsa_exception_int_div_zero 0
	.end_amdhsa_kernel

; __global__ void __launch_bounds__(512, 2) mega_fwd(Args A) {
amdhsa.kernels:
  - .agpr_count:     0
    .args:
      - .offset:         0
        .size:           192
        .value_kind:     by_value
      - .offset:         192
        .size:           4
        .value_kind:     hidden_block_count_x
      - .offset:         196
        .size:           4
        .value_kind:     hidden_block_count_y
      - .offset:         200
        .size:           4
        .value_kind:     hidden_block_count_z
      - .offset:         204
        .size:           2
        .value_kind:     hidden_group_size_x
      - .offset:         206
        .size:           2
        .value_kind:     hidden_group_size_y
      - .offset:         208
        .size:           2
        .value_kind:     hidden_group_size_z
      - .offset:         210
        .size:           2
        .value_kind:     hidden_remainder_x
      - .offset:         212
        .size:           2
        .value_kind:     hidden_remainder_y
      - .offset:         214
        .size:           2
        .value_kind:     hidden_remainder_z
      - .offset:         232
        .size:           8
        .value_kind:     hidden_global_offset_x
      - .offset:         240
        .size:           8
        .value_kind:     hidden_global_offset_y
      - .offset:         248
        .size:           8
        .value_kind:     hidden_global_offset_z
      - .offset:         256
        .size:           2
        .value_kind:     hidden_grid_dims
      - .offset:         280
        .size:           8
        .value_kind:     hidden_multigrid_sync_arg
      - .offset:         312
        .size:           4
        .value_kind:     hidden_dynamic_lds_size
    .group_segment_fixed_size: 0
    .kernarg_segment_align: 8
    .kernarg_segment_size: 448
    .language:       OpenCL C
    .language_version:
      - 2
      - 0
    .max_flat_workgroup_size: 512
    .name:           _Z8mega_fwd4Args
    .private_segment_fixed_size: 0
    .sgpr_count:     104
    .sgpr_spill_count: 5
    .symbol:         _Z8mega_fwd4Args.kd
    .uniform_work_group_size: 1
    .uses_dynamic_stack: false
    .vgpr_count:     256
    .vgpr_spill_count: 0
    .wavefront_size: 64
